# v75 stack with two staggered poll loads in flight in the grid-barrier wait (shorter worst-case detection)
# baseline (speedup 1.0000x reference)
.Lsb0_poll:
	s_mov_b32 s8, 0
	global_load_dword v3, v2, s[44:45] offset:1024 sc1
	s_sleep 12
.Lsb0_pl:
	global_load_dword v5, v2, s[44:45] offset:1024 sc1
	s_waitcnt vmcnt(1)
	v_readfirstlane_b32 s2, v3
	s_nop 1
	s_cmp_ge_u32 s2, s9
	s_cbranch_scc1 .Lsb0_pd
	global_load_dword v3, v2, s[44:45] offset:1024 sc1
	s_waitcnt vmcnt(1)
	v_readfirstlane_b32 s2, v5
	s_nop 1
	s_cmp_ge_u32 s2, s9
	s_cbranch_scc1 .Lsb0_pd
	s_add_u32 s8, s8, 1
	s_cmp_lt_u32 s8, 0x4000
	s_cbranch_scc0 .Lsb0_pd
	s_branch .Lsb0_pl
